# P1 epilogue sigmoid gates: 1/(1+e) via v_rcp_f32 + one Newton step (denominator clamped to FLT_MAX) instead of the 12-instruction IEEE division sequence; result still rounded to bf16 as before
# speedup vs baseline: 1.0626x; 1.0080x over previous
.LBB0_208:
	v_cndmask_b32_e64 v136, 0, 1, s[50:51]
	v_cmp_ne_u32_e64 s[14:15], 1, v136
	s_andn2_b64 vcc, exec, s[50:51]
	s_cbranch_vccnz .LBB0_210
	v_mul_f32_e32 v134, 0xbfb8aa3b, v134
	v_mul_f32_e32 v135, 0xbfb8aa3b, v135
	v_exp_f32_e32 v134, v134
	v_exp_f32_e32 v135, v135
	v_mul_f32_e32 v132, 0xbfb8aa3b, v132
	v_mul_f32_e32 v133, 0xbfb8aa3b, v133
	v_exp_f32_e32 v132, v132
	v_pk_add_f32 v[134:135], v[134:135], 1.0 op_sel_hi:[1,0]
	v_exp_f32_e32 v133, v133
	s_nop 0
	v_pk_add_f32 v[132:133], v[132:133], 1.0 op_sel_hi:[1,0]
	v_mul_f32_e32 v130, 0xbfb8aa3b, v130
	v_mul_f32_e32 v131, 0xbfb8aa3b, v131
	v_min_f32_e32 v135, 0x7f7fffff, v135
	v_rcp_f32_e32 v136, v135
	s_nop 0
	v_fma_f32 v135, -v135, v136, 1.0
	v_fma_f32 v135, v135, v136, v136
	v_exp_f32_e32 v130, v130
	v_exp_f32_e32 v131, v131
	v_mul_f32_e32 v128, 0xbfb8aa3b, v128
	v_min_f32_e32 v134, 0x7f7fffff, v134
	v_rcp_f32_e32 v136, v134
	s_nop 0
	v_fma_f32 v134, -v134, v136, 1.0
	v_fma_f32 v134, v134, v136, v136
	v_pk_add_f32 v[130:131], v[130:131], 1.0 op_sel_hi:[1,0]
	v_mul_f32_e32 v129, 0xbfb8aa3b, v129
	v_exp_f32_e32 v128, v128
	v_min_f32_e32 v133, 0x7f7fffff, v133
	v_rcp_f32_e32 v136, v133
	s_nop 0
	v_fma_f32 v133, -v133, v136, 1.0
	v_fma_f32 v133, v133, v136, v136
	v_exp_f32_e32 v129, v129
	v_min_f32_e32 v132, 0x7f7fffff, v132
	v_rcp_f32_e32 v136, v132
	s_nop 0
	v_fma_f32 v132, -v132, v136, 1.0
	v_fma_f32 v132, v132, v136, v136
	v_pk_add_f32 v[128:129], v[128:129], 1.0 op_sel_hi:[1,0]
	v_min_f32_e32 v131, 0x7f7fffff, v131
	v_rcp_f32_e32 v136, v131
	s_nop 0
	v_fma_f32 v131, -v131, v136, 1.0
	v_fma_f32 v131, v131, v136, v136
	v_min_f32_e32 v130, 0x7f7fffff, v130
	v_rcp_f32_e32 v136, v130
	s_nop 0
	v_fma_f32 v130, -v130, v136, 1.0
	v_fma_f32 v130, v130, v136, v136
	v_min_f32_e32 v129, 0x7f7fffff, v129
	v_rcp_f32_e32 v136, v129
	s_nop 0
	v_fma_f32 v129, -v129, v136, 1.0
	v_fma_f32 v129, v129, v136, v136
	v_min_f32_e32 v128, 0x7f7fffff, v128
	v_rcp_f32_e32 v136, v128
	s_nop 0
	v_fma_f32 v128, -v128, v136, 1.0
	v_fma_f32 v128, v128, v136, v136

.LBB0_226:
	s_and_b64 vcc, exec, s[14:15]
	s_cbranch_vccnz .LBB0_228
	v_mul_f32_e32 v118, 0xbfb8aa3b, v118
	v_mul_f32_e32 v119, 0xbfb8aa3b, v119
	v_exp_f32_e32 v118, v118
	v_exp_f32_e32 v119, v119
	v_mul_f32_e32 v116, 0xbfb8aa3b, v116
	v_mul_f32_e32 v117, 0xbfb8aa3b, v117
	v_exp_f32_e32 v116, v116
	v_pk_add_f32 v[118:119], v[118:119], 1.0 op_sel_hi:[1,0]
	v_exp_f32_e32 v117, v117
	s_nop 0
	v_pk_add_f32 v[116:117], v[116:117], 1.0 op_sel_hi:[1,0]
	v_mul_f32_e32 v114, 0xbfb8aa3b, v114
	v_mul_f32_e32 v115, 0xbfb8aa3b, v115
	v_min_f32_e32 v119, 0x7f7fffff, v119
	v_rcp_f32_e32 v120, v119
	s_nop 0
	v_fma_f32 v119, -v119, v120, 1.0
	v_fma_f32 v119, v119, v120, v120
	v_exp_f32_e32 v114, v114
	v_exp_f32_e32 v115, v115
	v_mul_f32_e32 v112, 0xbfb8aa3b, v112
	v_min_f32_e32 v118, 0x7f7fffff, v118
	v_rcp_f32_e32 v120, v118
	s_nop 0
	v_fma_f32 v118, -v118, v120, 1.0
	v_fma_f32 v118, v118, v120, v120
	v_pk_add_f32 v[114:115], v[114:115], 1.0 op_sel_hi:[1,0]
	v_mul_f32_e32 v113, 0xbfb8aa3b, v113
	v_exp_f32_e32 v112, v112
	v_min_f32_e32 v117, 0x7f7fffff, v117
	v_rcp_f32_e32 v120, v117
	s_nop 0
	v_fma_f32 v117, -v117, v120, 1.0
	v_fma_f32 v117, v117, v120, v120
	v_exp_f32_e32 v113, v113
	v_min_f32_e32 v116, 0x7f7fffff, v116
	v_rcp_f32_e32 v120, v116
	s_nop 0
	v_fma_f32 v116, -v116, v120, 1.0
	v_fma_f32 v116, v116, v120, v120
	v_pk_add_f32 v[112:113], v[112:113], 1.0 op_sel_hi:[1,0]
	v_min_f32_e32 v115, 0x7f7fffff, v115
	v_rcp_f32_e32 v120, v115
	s_nop 0
	v_fma_f32 v115, -v115, v120, 1.0
	v_fma_f32 v115, v115, v120, v120
	v_min_f32_e32 v114, 0x7f7fffff, v114
	v_rcp_f32_e32 v120, v114
	s_nop 0
	v_fma_f32 v114, -v114, v120, 1.0
	v_fma_f32 v114, v114, v120, v120
	v_min_f32_e32 v113, 0x7f7fffff, v113
	v_rcp_f32_e32 v120, v113
	s_nop 0
	v_fma_f32 v113, -v113, v120, 1.0
	v_fma_f32 v113, v113, v120, v120
	v_min_f32_e32 v112, 0x7f7fffff, v112
	v_rcp_f32_e32 v120, v112
	s_nop 0
	v_fma_f32 v112, -v112, v120, 1.0
	v_fma_f32 v112, v112, v120, v120

.LBB0_244:
	s_and_b64 vcc, exec, s[14:15]
	s_cbranch_vccnz .LBB0_246
	v_mul_f32_e32 v102, 0xbfb8aa3b, v102
	v_mul_f32_e32 v103, 0xbfb8aa3b, v103
	v_exp_f32_e32 v102, v102
	v_exp_f32_e32 v103, v103
	v_mul_f32_e32 v100, 0xbfb8aa3b, v100
	v_mul_f32_e32 v101, 0xbfb8aa3b, v101
	v_exp_f32_e32 v100, v100
	v_pk_add_f32 v[102:103], v[102:103], 1.0 op_sel_hi:[1,0]
	v_exp_f32_e32 v101, v101
	s_nop 0
	v_pk_add_f32 v[100:101], v[100:101], 1.0 op_sel_hi:[1,0]
	v_mul_f32_e32 v98, 0xbfb8aa3b, v98
	v_mul_f32_e32 v99, 0xbfb8aa3b, v99
	v_min_f32_e32 v103, 0x7f7fffff, v103
	v_rcp_f32_e32 v104, v103
	s_nop 0
	v_fma_f32 v103, -v103, v104, 1.0
	v_fma_f32 v103, v103, v104, v104
	v_exp_f32_e32 v98, v98
	v_exp_f32_e32 v99, v99
	v_mul_f32_e32 v96, 0xbfb8aa3b, v96
	v_min_f32_e32 v102, 0x7f7fffff, v102
	v_rcp_f32_e32 v104, v102
	s_nop 0
	v_fma_f32 v102, -v102, v104, 1.0
	v_fma_f32 v102, v102, v104, v104
	v_pk_add_f32 v[98:99], v[98:99], 1.0 op_sel_hi:[1,0]
	v_mul_f32_e32 v97, 0xbfb8aa3b, v97
	v_exp_f32_e32 v96, v96
	v_min_f32_e32 v101, 0x7f7fffff, v101
	v_rcp_f32_e32 v104, v101
	s_nop 0
	v_fma_f32 v101, -v101, v104, 1.0
	v_fma_f32 v101, v101, v104, v104
	v_exp_f32_e32 v97, v97
	v_min_f32_e32 v100, 0x7f7fffff, v100
	v_rcp_f32_e32 v104, v100
	s_nop 0
	v_fma_f32 v100, -v100, v104, 1.0
	v_fma_f32 v100, v100, v104, v104
	v_pk_add_f32 v[96:97], v[96:97], 1.0 op_sel_hi:[1,0]
	v_min_f32_e32 v99, 0x7f7fffff, v99
	v_rcp_f32_e32 v104, v99
	s_nop 0
	v_fma_f32 v99, -v99, v104, 1.0
	v_fma_f32 v99, v99, v104, v104
	v_min_f32_e32 v98, 0x7f7fffff, v98
	v_rcp_f32_e32 v104, v98
	s_nop 0
	v_fma_f32 v98, -v98, v104, 1.0
	v_fma_f32 v98, v98, v104, v104
	v_min_f32_e32 v97, 0x7f7fffff, v97
	v_rcp_f32_e32 v104, v97
	s_nop 0
	v_fma_f32 v97, -v97, v104, 1.0
	v_fma_f32 v97, v97, v104, v104
	v_min_f32_e32 v96, 0x7f7fffff, v96
	v_rcp_f32_e32 v104, v96
	s_nop 0
	v_fma_f32 v96, -v96, v104, 1.0
	v_fma_f32 v96, v96, v104, v104

.LBB0_262:
	s_and_b64 vcc, exec, s[14:15]
	s_cbranch_vccnz .LBB0_264
	v_mul_f32_e32 v86, 0xbfb8aa3b, v86
	v_mul_f32_e32 v87, 0xbfb8aa3b, v87
	v_exp_f32_e32 v86, v86
	v_exp_f32_e32 v87, v87
	v_mul_f32_e32 v84, 0xbfb8aa3b, v84
	v_mul_f32_e32 v85, 0xbfb8aa3b, v85
	v_exp_f32_e32 v84, v84
	v_pk_add_f32 v[86:87], v[86:87], 1.0 op_sel_hi:[1,0]
	v_exp_f32_e32 v85, v85
	s_nop 0
	v_pk_add_f32 v[84:85], v[84:85], 1.0 op_sel_hi:[1,0]
	v_mul_f32_e32 v82, 0xbfb8aa3b, v82
	v_mul_f32_e32 v83, 0xbfb8aa3b, v83
	v_min_f32_e32 v87, 0x7f7fffff, v87
	v_rcp_f32_e32 v88, v87
	s_nop 0
	v_fma_f32 v87, -v87, v88, 1.0
	v_fma_f32 v87, v87, v88, v88
	v_exp_f32_e32 v82, v82
	v_exp_f32_e32 v83, v83
	v_mul_f32_e32 v80, 0xbfb8aa3b, v80
	v_min_f32_e32 v86, 0x7f7fffff, v86
	v_rcp_f32_e32 v88, v86
	s_nop 0
	v_fma_f32 v86, -v86, v88, 1.0
	v_fma_f32 v86, v86, v88, v88
	v_pk_add_f32 v[82:83], v[82:83], 1.0 op_sel_hi:[1,0]
	v_mul_f32_e32 v81, 0xbfb8aa3b, v81
	v_exp_f32_e32 v80, v80
	v_min_f32_e32 v85, 0x7f7fffff, v85
	v_rcp_f32_e32 v88, v85
	s_nop 0
	v_fma_f32 v85, -v85, v88, 1.0
	v_fma_f32 v85, v85, v88, v88
	v_exp_f32_e32 v81, v81
	v_min_f32_e32 v84, 0x7f7fffff, v84
	v_rcp_f32_e32 v88, v84
	s_nop 0
	v_fma_f32 v84, -v84, v88, 1.0
	v_fma_f32 v84, v84, v88, v88
	v_pk_add_f32 v[80:81], v[80:81], 1.0 op_sel_hi:[1,0]
	v_min_f32_e32 v83, 0x7f7fffff, v83
	v_rcp_f32_e32 v88, v83
	s_nop 0
	v_fma_f32 v83, -v83, v88, 1.0
	v_fma_f32 v83, v83, v88, v88
	v_min_f32_e32 v82, 0x7f7fffff, v82
	v_rcp_f32_e32 v88, v82
	s_nop 0
	v_fma_f32 v82, -v82, v88, 1.0
	v_fma_f32 v82, v82, v88, v88
	v_min_f32_e32 v81, 0x7f7fffff, v81
	v_rcp_f32_e32 v88, v81
	s_nop 0
	v_fma_f32 v81, -v81, v88, 1.0
	v_fma_f32 v81, v81, v88, v88
	v_min_f32_e32 v80, 0x7f7fffff, v80
	v_rcp_f32_e32 v88, v80
	s_nop 0
	v_fma_f32 v80, -v80, v88, 1.0
	v_fma_f32 v80, v80, v88, v88

.LBB0_280:
	s_and_b64 vcc, exec, s[14:15]
	s_cbranch_vccnz .LBB0_282
	v_mul_f32_e32 v70, 0xbfb8aa3b, v70
	v_mul_f32_e32 v71, 0xbfb8aa3b, v71
	v_exp_f32_e32 v70, v70
	v_exp_f32_e32 v71, v71
	v_mul_f32_e32 v68, 0xbfb8aa3b, v68
	v_mul_f32_e32 v69, 0xbfb8aa3b, v69
	v_exp_f32_e32 v68, v68
	v_pk_add_f32 v[70:71], v[70:71], 1.0 op_sel_hi:[1,0]
	v_exp_f32_e32 v69, v69
	s_nop 0
	v_pk_add_f32 v[68:69], v[68:69], 1.0 op_sel_hi:[1,0]
	v_mul_f32_e32 v66, 0xbfb8aa3b, v66
	v_mul_f32_e32 v67, 0xbfb8aa3b, v67
	v_min_f32_e32 v71, 0x7f7fffff, v71
	v_rcp_f32_e32 v72, v71
	s_nop 0
	v_fma_f32 v71, -v71, v72, 1.0
	v_fma_f32 v71, v71, v72, v72
	v_exp_f32_e32 v66, v66
	v_exp_f32_e32 v67, v67
	v_mul_f32_e32 v64, 0xbfb8aa3b, v64
	v_min_f32_e32 v70, 0x7f7fffff, v70
	v_rcp_f32_e32 v72, v70
	s_nop 0
	v_fma_f32 v70, -v70, v72, 1.0
	v_fma_f32 v70, v70, v72, v72
	v_pk_add_f32 v[66:67], v[66:67], 1.0 op_sel_hi:[1,0]
	v_mul_f32_e32 v65, 0xbfb8aa3b, v65
	v_exp_f32_e32 v64, v64
	v_min_f32_e32 v69, 0x7f7fffff, v69
	v_rcp_f32_e32 v72, v69
	s_nop 0
	v_fma_f32 v69, -v69, v72, 1.0
	v_fma_f32 v69, v69, v72, v72
	v_exp_f32_e32 v65, v65
	v_min_f32_e32 v68, 0x7f7fffff, v68
	v_rcp_f32_e32 v72, v68
	s_nop 0
	v_fma_f32 v68, -v68, v72, 1.0
	v_fma_f32 v68, v68, v72, v72
	v_pk_add_f32 v[64:65], v[64:65], 1.0 op_sel_hi:[1,0]
	v_min_f32_e32 v67, 0x7f7fffff, v67
	v_rcp_f32_e32 v72, v67
	s_nop 0
	v_fma_f32 v67, -v67, v72, 1.0
	v_fma_f32 v67, v67, v72, v72
	v_min_f32_e32 v66, 0x7f7fffff, v66
	v_rcp_f32_e32 v72, v66
	s_nop 0
	v_fma_f32 v66, -v66, v72, 1.0
	v_fma_f32 v66, v66, v72, v72
	v_min_f32_e32 v65, 0x7f7fffff, v65
	v_rcp_f32_e32 v72, v65
	s_nop 0
	v_fma_f32 v65, -v65, v72, 1.0
	v_fma_f32 v65, v65, v72, v72
	v_min_f32_e32 v64, 0x7f7fffff, v64
	v_rcp_f32_e32 v72, v64
	s_nop 0
	v_fma_f32 v64, -v64, v72, 1.0
	v_fma_f32 v64, v64, v72, v72

.LBB0_298:
	s_and_b64 vcc, exec, s[14:15]
	s_cbranch_vccnz .LBB0_300
	v_mul_f32_e32 v46, 0xbfb8aa3b, v46
	v_mul_f32_e32 v47, 0xbfb8aa3b, v47
	v_exp_f32_e32 v46, v46
	v_exp_f32_e32 v47, v47
	v_mul_f32_e32 v44, 0xbfb8aa3b, v44
	v_mul_f32_e32 v45, 0xbfb8aa3b, v45
	v_exp_f32_e32 v44, v44
	v_pk_add_f32 v[46:47], v[46:47], 1.0 op_sel_hi:[1,0]
	v_exp_f32_e32 v45, v45
	s_nop 0
	v_pk_add_f32 v[44:45], v[44:45], 1.0 op_sel_hi:[1,0]
	v_mul_f32_e32 v42, 0xbfb8aa3b, v42
	v_mul_f32_e32 v43, 0xbfb8aa3b, v43
	v_min_f32_e32 v47, 0x7f7fffff, v47
	v_rcp_f32_e32 v56, v47
	s_nop 0
	v_fma_f32 v47, -v47, v56, 1.0
	v_fma_f32 v47, v47, v56, v56
	v_exp_f32_e32 v42, v42
	v_exp_f32_e32 v43, v43
	v_mul_f32_e32 v40, 0xbfb8aa3b, v40
	v_min_f32_e32 v46, 0x7f7fffff, v46
	v_rcp_f32_e32 v56, v46
	s_nop 0
	v_fma_f32 v46, -v46, v56, 1.0
	v_fma_f32 v46, v46, v56, v56
	v_pk_add_f32 v[42:43], v[42:43], 1.0 op_sel_hi:[1,0]
	v_mul_f32_e32 v41, 0xbfb8aa3b, v41
	v_exp_f32_e32 v40, v40
	v_min_f32_e32 v45, 0x7f7fffff, v45
	v_rcp_f32_e32 v56, v45
	s_nop 0
	v_fma_f32 v45, -v45, v56, 1.0
	v_fma_f32 v45, v45, v56, v56
	v_exp_f32_e32 v41, v41
	v_min_f32_e32 v44, 0x7f7fffff, v44
	v_rcp_f32_e32 v56, v44
	s_nop 0
	v_fma_f32 v44, -v44, v56, 1.0
	v_fma_f32 v44, v44, v56, v56
	v_pk_add_f32 v[40:41], v[40:41], 1.0 op_sel_hi:[1,0]
	v_min_f32_e32 v43, 0x7f7fffff, v43
	v_rcp_f32_e32 v56, v43
	s_nop 0
	v_fma_f32 v43, -v43, v56, 1.0
	v_fma_f32 v43, v43, v56, v56
	v_min_f32_e32 v42, 0x7f7fffff, v42
	v_rcp_f32_e32 v56, v42
	s_nop 0
	v_fma_f32 v42, -v42, v56, 1.0
	v_fma_f32 v42, v42, v56, v56
	v_min_f32_e32 v41, 0x7f7fffff, v41
	v_rcp_f32_e32 v56, v41
	s_nop 0
	v_fma_f32 v41, -v41, v56, 1.0
	v_fma_f32 v41, v41, v56, v56
	v_min_f32_e32 v40, 0x7f7fffff, v40
	v_rcp_f32_e32 v56, v40
	s_nop 0
	v_fma_f32 v40, -v40, v56, 1.0
	v_fma_f32 v40, v40, v56, v56

.LBB0_316:
	s_and_b64 vcc, exec, s[14:15]
	s_cbranch_vccnz .LBB0_318
	v_mul_f32_e32 v30, 0xbfb8aa3b, v30
	v_mul_f32_e32 v31, 0xbfb8aa3b, v31
	v_exp_f32_e32 v30, v30
	v_exp_f32_e32 v31, v31
	v_mul_f32_e32 v28, 0xbfb8aa3b, v28
	v_mul_f32_e32 v29, 0xbfb8aa3b, v29
	v_exp_f32_e32 v28, v28
	v_pk_add_f32 v[30:31], v[30:31], 1.0 op_sel_hi:[1,0]
	v_exp_f32_e32 v29, v29
	s_nop 0
	v_pk_add_f32 v[28:29], v[28:29], 1.0 op_sel_hi:[1,0]
	v_mul_f32_e32 v26, 0xbfb8aa3b, v26
	v_mul_f32_e32 v27, 0xbfb8aa3b, v27
	v_min_f32_e32 v31, 0x7f7fffff, v31
	v_rcp_f32_e32 v32, v31
	s_nop 0
	v_fma_f32 v31, -v31, v32, 1.0
	v_fma_f32 v31, v31, v32, v32
	v_exp_f32_e32 v26, v26
	v_exp_f32_e32 v27, v27
	v_mul_f32_e32 v24, 0xbfb8aa3b, v24
	v_min_f32_e32 v30, 0x7f7fffff, v30
	v_rcp_f32_e32 v32, v30
	s_nop 0
	v_fma_f32 v30, -v30, v32, 1.0
	v_fma_f32 v30, v30, v32, v32
	v_pk_add_f32 v[26:27], v[26:27], 1.0 op_sel_hi:[1,0]
	v_mul_f32_e32 v25, 0xbfb8aa3b, v25
	v_exp_f32_e32 v24, v24
	v_min_f32_e32 v29, 0x7f7fffff, v29
	v_rcp_f32_e32 v32, v29
	s_nop 0
	v_fma_f32 v29, -v29, v32, 1.0
	v_fma_f32 v29, v29, v32, v32
	v_exp_f32_e32 v25, v25
	v_min_f32_e32 v28, 0x7f7fffff, v28
	v_rcp_f32_e32 v32, v28
	s_nop 0
	v_fma_f32 v28, -v28, v32, 1.0
	v_fma_f32 v28, v28, v32, v32
	v_pk_add_f32 v[24:25], v[24:25], 1.0 op_sel_hi:[1,0]
	v_min_f32_e32 v27, 0x7f7fffff, v27
	v_rcp_f32_e32 v32, v27
	s_nop 0
	v_fma_f32 v27, -v27, v32, 1.0
	v_fma_f32 v27, v27, v32, v32
	v_min_f32_e32 v26, 0x7f7fffff, v26
	v_rcp_f32_e32 v32, v26
	s_nop 0
	v_fma_f32 v26, -v26, v32, 1.0
	v_fma_f32 v26, v26, v32, v32
	v_min_f32_e32 v25, 0x7f7fffff, v25
	v_rcp_f32_e32 v32, v25
	s_nop 0
	v_fma_f32 v25, -v25, v32, 1.0
	v_fma_f32 v25, v25, v32, v32
	v_min_f32_e32 v24, 0x7f7fffff, v24
	v_rcp_f32_e32 v32, v24
	s_nop 0
	v_fma_f32 v24, -v24, v32, 1.0
	v_fma_f32 v24, v24, v32, v32

.LBB0_334:
	s_and_b64 vcc, exec, s[14:15]
	s_cbranch_vccnz .LBB0_336
	v_mul_f32_e32 v14, 0xbfb8aa3b, v14
	v_mul_f32_e32 v15, 0xbfb8aa3b, v15
	v_exp_f32_e32 v14, v14
	v_exp_f32_e32 v15, v15
	v_mul_f32_e32 v12, 0xbfb8aa3b, v12
	v_mul_f32_e32 v13, 0xbfb8aa3b, v13
	v_exp_f32_e32 v12, v12
	v_pk_add_f32 v[14:15], v[14:15], 1.0 op_sel_hi:[1,0]
	v_exp_f32_e32 v13, v13
	s_nop 0
	v_pk_add_f32 v[12:13], v[12:13], 1.0 op_sel_hi:[1,0]
	v_mul_f32_e32 v10, 0xbfb8aa3b, v10
	v_mul_f32_e32 v11, 0xbfb8aa3b, v11
	v_min_f32_e32 v15, 0x7f7fffff, v15
	v_rcp_f32_e32 v16, v15
	s_nop 0
	v_fma_f32 v15, -v15, v16, 1.0
	v_fma_f32 v15, v15, v16, v16
	v_exp_f32_e32 v10, v10
	v_exp_f32_e32 v11, v11
	v_mul_f32_e32 v8, 0xbfb8aa3b, v8
	v_min_f32_e32 v14, 0x7f7fffff, v14
	v_rcp_f32_e32 v16, v14
	s_nop 0
	v_fma_f32 v14, -v14, v16, 1.0
	v_fma_f32 v14, v14, v16, v16
	v_pk_add_f32 v[10:11], v[10:11], 1.0 op_sel_hi:[1,0]
	v_mul_f32_e32 v9, 0xbfb8aa3b, v9
	v_exp_f32_e32 v8, v8
	v_min_f32_e32 v13, 0x7f7fffff, v13
	v_rcp_f32_e32 v16, v13
	s_nop 0
	v_fma_f32 v13, -v13, v16, 1.0
	v_fma_f32 v13, v13, v16, v16
	v_exp_f32_e32 v9, v9
	v_min_f32_e32 v12, 0x7f7fffff, v12
	v_rcp_f32_e32 v16, v12
	s_nop 0
	v_fma_f32 v12, -v12, v16, 1.0
	v_fma_f32 v12, v12, v16, v16
	v_pk_add_f32 v[8:9], v[8:9], 1.0 op_sel_hi:[1,0]
	v_min_f32_e32 v11, 0x7f7fffff, v11
	v_rcp_f32_e32 v16, v11
	s_nop 0
	v_fma_f32 v11, -v11, v16, 1.0
	v_fma_f32 v11, v11, v16, v16
	v_min_f32_e32 v10, 0x7f7fffff, v10
	v_rcp_f32_e32 v16, v10
	s_nop 0
	v_fma_f32 v10, -v10, v16, 1.0
	v_fma_f32 v10, v10, v16, v16
	v_min_f32_e32 v9, 0x7f7fffff, v9
	v_rcp_f32_e32 v16, v9
	s_nop 0
	v_fma_f32 v9, -v9, v16, 1.0
	v_fma_f32 v9, v9, v16, v16
	v_min_f32_e32 v8, 0x7f7fffff, v8
	v_rcp_f32_e32 v16, v8
	s_nop 0
	v_fma_f32 v8, -v8, v16, 1.0
	v_fma_f32 v8, v8, v16, v16

.LBB0_351:
	v_mul_f32_e32 v126, 0xbfb8aa3b, v126
	v_mul_f32_e32 v127, 0xbfb8aa3b, v127
	v_exp_f32_e32 v126, v126
	v_exp_f32_e32 v127, v127
	v_mul_f32_e32 v124, 0xbfb8aa3b, v124
	v_mul_f32_e32 v125, 0xbfb8aa3b, v125
	v_exp_f32_e32 v124, v124
	v_pk_add_f32 v[126:127], v[126:127], 1.0 op_sel_hi:[1,0]
	v_exp_f32_e32 v125, v125
	s_nop 0
	v_pk_add_f32 v[124:125], v[124:125], 1.0 op_sel_hi:[1,0]
	v_mul_f32_e32 v122, 0xbfb8aa3b, v122
	v_mul_f32_e32 v123, 0xbfb8aa3b, v123
	v_min_f32_e32 v127, 0x7f7fffff, v127
	v_rcp_f32_e32 v128, v127
	s_nop 0
	v_fma_f32 v127, -v127, v128, 1.0
	v_fma_f32 v127, v127, v128, v128
	v_exp_f32_e32 v122, v122
	v_exp_f32_e32 v123, v123
	v_mul_f32_e32 v120, 0xbfb8aa3b, v120
	v_min_f32_e32 v126, 0x7f7fffff, v126
	v_rcp_f32_e32 v128, v126
	s_nop 0
	v_fma_f32 v126, -v126, v128, 1.0
	v_fma_f32 v126, v126, v128, v128
	v_pk_add_f32 v[122:123], v[122:123], 1.0 op_sel_hi:[1,0]
	v_mul_f32_e32 v121, 0xbfb8aa3b, v121
	v_exp_f32_e32 v120, v120
	v_min_f32_e32 v125, 0x7f7fffff, v125
	v_rcp_f32_e32 v128, v125
	s_nop 0
	v_fma_f32 v125, -v125, v128, 1.0
	v_fma_f32 v125, v125, v128, v128
	v_exp_f32_e32 v121, v121
	v_min_f32_e32 v124, 0x7f7fffff, v124
	v_rcp_f32_e32 v128, v124
	s_nop 0
	v_fma_f32 v124, -v124, v128, 1.0
	v_fma_f32 v124, v124, v128, v128
	v_pk_add_f32 v[120:121], v[120:121], 1.0 op_sel_hi:[1,0]
	v_min_f32_e32 v123, 0x7f7fffff, v123
	v_rcp_f32_e32 v128, v123
	s_nop 0
	v_fma_f32 v123, -v123, v128, 1.0
	v_fma_f32 v123, v123, v128, v128
	v_min_f32_e32 v122, 0x7f7fffff, v122
	v_rcp_f32_e32 v128, v122
	s_nop 0
	v_fma_f32 v122, -v122, v128, 1.0
	v_fma_f32 v122, v122, v128, v128
	v_min_f32_e32 v121, 0x7f7fffff, v121
	v_rcp_f32_e32 v128, v121
	s_nop 0
	v_fma_f32 v121, -v121, v128, 1.0
	v_fma_f32 v121, v121, v128, v128
	v_div_scale_f32 v128, s[18:19], v120, v120, 1.0
	v_rcp_f32_e32 v129, v128
	s_nop 0
	v_fma_f32 v130, -v128, v129, 1.0
	v_fmac_f32_e32 v129, v130, v129
	v_div_scale_f32 v130, vcc, 1.0, v120, 1.0
	v_mul_f32_e32 v131, v130, v129
	v_fma_f32 v134, -v128, v131, v130
	v_fmac_f32_e32 v131, v134, v129
	v_fma_f32 v128, -v128, v131, v130
	v_div_fmas_f32 v128, v128, v129, v131
	v_div_fixup_f32 v120, v128, v120, 1.0
	v_cndmask_b32_e64 v128, 0, 1, s[20:21]
	v_cmp_ne_u32_e64 s[18:19], 1, v128
	s_andn2_b64 vcc, exec, s[20:21]
	s_cbranch_vccz .LBB0_219
	s_branch .LBB0_220

.LBB0_353:
	v_mul_f32_e32 v110, 0xbfb8aa3b, v110
	v_mul_f32_e32 v111, 0xbfb8aa3b, v111
	v_exp_f32_e32 v110, v110
	v_exp_f32_e32 v111, v111
	v_mul_f32_e32 v108, 0xbfb8aa3b, v108
	v_mul_f32_e32 v109, 0xbfb8aa3b, v109
	v_exp_f32_e32 v108, v108
	v_pk_add_f32 v[110:111], v[110:111], 1.0 op_sel_hi:[1,0]
	v_exp_f32_e32 v109, v109
	s_nop 0
	v_pk_add_f32 v[108:109], v[108:109], 1.0 op_sel_hi:[1,0]
	v_mul_f32_e32 v106, 0xbfb8aa3b, v106
	v_mul_f32_e32 v107, 0xbfb8aa3b, v107
	v_min_f32_e32 v111, 0x7f7fffff, v111
	v_rcp_f32_e32 v113, v111
	s_nop 0
	v_fma_f32 v111, -v111, v113, 1.0
	v_fma_f32 v111, v111, v113, v113
	v_exp_f32_e32 v106, v106
	v_exp_f32_e32 v107, v107
	v_mul_f32_e32 v104, 0xbfb8aa3b, v104
	v_min_f32_e32 v110, 0x7f7fffff, v110
	v_rcp_f32_e32 v113, v110
	s_nop 0
	v_fma_f32 v110, -v110, v113, 1.0
	v_fma_f32 v110, v110, v113, v113
	v_pk_add_f32 v[106:107], v[106:107], 1.0 op_sel_hi:[1,0]
	v_mul_f32_e32 v105, 0xbfb8aa3b, v105
	v_exp_f32_e32 v104, v104
	v_min_f32_e32 v109, 0x7f7fffff, v109
	v_rcp_f32_e32 v113, v109
	s_nop 0
	v_fma_f32 v109, -v109, v113, 1.0
	v_fma_f32 v109, v109, v113, v113
	v_exp_f32_e32 v105, v105
	v_min_f32_e32 v108, 0x7f7fffff, v108
	v_rcp_f32_e32 v113, v108
	s_nop 0
	v_fma_f32 v108, -v108, v113, 1.0
	v_fma_f32 v108, v108, v113, v113
	v_pk_add_f32 v[104:105], v[104:105], 1.0 op_sel_hi:[1,0]
	v_min_f32_e32 v107, 0x7f7fffff, v107
	v_rcp_f32_e32 v113, v107
	s_nop 0
	v_fma_f32 v107, -v107, v113, 1.0
	v_fma_f32 v107, v107, v113, v113
	v_min_f32_e32 v106, 0x7f7fffff, v106
	v_rcp_f32_e32 v113, v106
	s_nop 0
	v_fma_f32 v106, -v106, v113, 1.0
	v_fma_f32 v106, v106, v113, v113
	v_min_f32_e32 v105, 0x7f7fffff, v105
	v_rcp_f32_e32 v113, v105
	s_nop 0
	v_fma_f32 v105, -v105, v113, 1.0
	v_fma_f32 v105, v105, v113, v113
	v_div_scale_f32 v113, s[20:21], v104, v104, 1.0
	v_rcp_f32_e32 v114, v113
	s_nop 0
	v_fma_f32 v115, -v113, v114, 1.0
	v_fmac_f32_e32 v114, v115, v114
	v_div_scale_f32 v115, vcc, 1.0, v104, 1.0
	v_mul_f32_e32 v118, v115, v114
	v_fma_f32 v119, -v113, v118, v115
	v_fmac_f32_e32 v118, v119, v114
	v_fma_f32 v113, -v113, v118, v115
	v_div_fmas_f32 v113, v113, v114, v118
	v_div_fixup_f32 v104, v113, v104, 1.0
	s_and_b64 vcc, exec, s[18:19]
	s_cbranch_vccz .LBB0_237
	s_branch .LBB0_238

.LBB0_355:
	v_mul_f32_e32 v94, 0xbfb8aa3b, v94
	v_mul_f32_e32 v95, 0xbfb8aa3b, v95
	v_exp_f32_e32 v94, v94
	v_exp_f32_e32 v95, v95
	v_mul_f32_e32 v92, 0xbfb8aa3b, v92
	v_mul_f32_e32 v93, 0xbfb8aa3b, v93
	v_exp_f32_e32 v92, v92
	v_pk_add_f32 v[94:95], v[94:95], 1.0 op_sel_hi:[1,0]
	v_exp_f32_e32 v93, v93
	s_nop 0
	v_pk_add_f32 v[92:93], v[92:93], 1.0 op_sel_hi:[1,0]
	v_mul_f32_e32 v90, 0xbfb8aa3b, v90
	v_mul_f32_e32 v91, 0xbfb8aa3b, v91
	v_min_f32_e32 v95, 0x7f7fffff, v95
	v_rcp_f32_e32 v96, v95
	s_nop 0
	v_fma_f32 v95, -v95, v96, 1.0
	v_fma_f32 v95, v95, v96, v96
	v_exp_f32_e32 v90, v90
	v_exp_f32_e32 v91, v91
	v_mul_f32_e32 v88, 0xbfb8aa3b, v88
	v_min_f32_e32 v94, 0x7f7fffff, v94
	v_rcp_f32_e32 v96, v94
	s_nop 0
	v_fma_f32 v94, -v94, v96, 1.0
	v_fma_f32 v94, v94, v96, v96
	v_pk_add_f32 v[90:91], v[90:91], 1.0 op_sel_hi:[1,0]
	v_mul_f32_e32 v89, 0xbfb8aa3b, v89
	v_exp_f32_e32 v88, v88
	v_min_f32_e32 v93, 0x7f7fffff, v93
	v_rcp_f32_e32 v96, v93
	s_nop 0
	v_fma_f32 v93, -v93, v96, 1.0
	v_fma_f32 v93, v93, v96, v96
	v_exp_f32_e32 v89, v89
	v_min_f32_e32 v92, 0x7f7fffff, v92
	v_rcp_f32_e32 v96, v92
	s_nop 0
	v_fma_f32 v92, -v92, v96, 1.0
	v_fma_f32 v92, v92, v96, v96
	v_pk_add_f32 v[88:89], v[88:89], 1.0 op_sel_hi:[1,0]
	v_min_f32_e32 v91, 0x7f7fffff, v91
	v_rcp_f32_e32 v96, v91
	s_nop 0
	v_fma_f32 v91, -v91, v96, 1.0
	v_fma_f32 v91, v91, v96, v96
	v_min_f32_e32 v90, 0x7f7fffff, v90
	v_rcp_f32_e32 v96, v90
	s_nop 0
	v_fma_f32 v90, -v90, v96, 1.0
	v_fma_f32 v90, v90, v96, v96
	v_min_f32_e32 v89, 0x7f7fffff, v89
	v_rcp_f32_e32 v96, v89
	s_nop 0
	v_fma_f32 v89, -v89, v96, 1.0
	v_fma_f32 v89, v89, v96, v96
	v_div_scale_f32 v96, s[20:21], v88, v88, 1.0
	v_rcp_f32_e32 v97, v96
	s_nop 0
	v_fma_f32 v98, -v96, v97, 1.0
	v_fmac_f32_e32 v97, v98, v97
	v_div_scale_f32 v98, vcc, 1.0, v88, 1.0
	v_mul_f32_e32 v99, v98, v97
	v_fma_f32 v102, -v96, v99, v98
	v_fmac_f32_e32 v99, v102, v97
	v_fma_f32 v96, -v96, v99, v98
	v_div_fmas_f32 v96, v96, v97, v99
	v_div_fixup_f32 v88, v96, v88, 1.0
	s_and_b64 vcc, exec, s[18:19]
	s_cbranch_vccz .LBB0_255
	s_branch .LBB0_256

.LBB0_357:
	v_mul_f32_e32 v78, 0xbfb8aa3b, v78
	v_mul_f32_e32 v79, 0xbfb8aa3b, v79
	v_exp_f32_e32 v78, v78
	v_exp_f32_e32 v79, v79
	v_mul_f32_e32 v76, 0xbfb8aa3b, v76
	v_mul_f32_e32 v77, 0xbfb8aa3b, v77
	v_exp_f32_e32 v76, v76
	v_pk_add_f32 v[78:79], v[78:79], 1.0 op_sel_hi:[1,0]
	v_exp_f32_e32 v77, v77
	s_nop 0
	v_pk_add_f32 v[76:77], v[76:77], 1.0 op_sel_hi:[1,0]
	v_mul_f32_e32 v74, 0xbfb8aa3b, v74
	v_mul_f32_e32 v75, 0xbfb8aa3b, v75
	v_min_f32_e32 v79, 0x7f7fffff, v79
	v_rcp_f32_e32 v80, v79
	s_nop 0
	v_fma_f32 v79, -v79, v80, 1.0
	v_fma_f32 v79, v79, v80, v80
	v_exp_f32_e32 v74, v74
	v_exp_f32_e32 v75, v75
	v_mul_f32_e32 v72, 0xbfb8aa3b, v72
	v_min_f32_e32 v78, 0x7f7fffff, v78
	v_rcp_f32_e32 v80, v78
	s_nop 0
	v_fma_f32 v78, -v78, v80, 1.0
	v_fma_f32 v78, v78, v80, v80
	v_pk_add_f32 v[74:75], v[74:75], 1.0 op_sel_hi:[1,0]
	v_mul_f32_e32 v73, 0xbfb8aa3b, v73
	v_exp_f32_e32 v72, v72
	v_min_f32_e32 v77, 0x7f7fffff, v77
	v_rcp_f32_e32 v80, v77
	s_nop 0
	v_fma_f32 v77, -v77, v80, 1.0
	v_fma_f32 v77, v77, v80, v80
	v_exp_f32_e32 v73, v73
	v_min_f32_e32 v76, 0x7f7fffff, v76
	v_rcp_f32_e32 v80, v76
	s_nop 0
	v_fma_f32 v76, -v76, v80, 1.0
	v_fma_f32 v76, v76, v80, v80
	v_pk_add_f32 v[72:73], v[72:73], 1.0 op_sel_hi:[1,0]
	v_min_f32_e32 v75, 0x7f7fffff, v75
	v_rcp_f32_e32 v80, v75
	s_nop 0
	v_fma_f32 v75, -v75, v80, 1.0
	v_fma_f32 v75, v75, v80, v80
	v_min_f32_e32 v74, 0x7f7fffff, v74
	v_rcp_f32_e32 v80, v74
	s_nop 0
	v_fma_f32 v74, -v74, v80, 1.0
	v_fma_f32 v74, v74, v80, v80
	v_min_f32_e32 v73, 0x7f7fffff, v73
	v_rcp_f32_e32 v80, v73
	s_nop 0
	v_fma_f32 v73, -v73, v80, 1.0
	v_fma_f32 v73, v73, v80, v80
	v_div_scale_f32 v80, s[20:21], v72, v72, 1.0
	v_rcp_f32_e32 v81, v80
	s_nop 0
	v_fma_f32 v82, -v80, v81, 1.0
	v_fmac_f32_e32 v81, v82, v81
	v_div_scale_f32 v82, vcc, 1.0, v72, 1.0
	v_mul_f32_e32 v83, v82, v81
	v_fma_f32 v86, -v80, v83, v82
	v_fmac_f32_e32 v83, v86, v81
	v_fma_f32 v80, -v80, v83, v82
	v_div_fmas_f32 v80, v80, v81, v83
	v_div_fixup_f32 v72, v80, v72, 1.0
	s_and_b64 vcc, exec, s[18:19]
	s_cbranch_vccz .LBB0_273
	s_branch .LBB0_274

.LBB0_359:
	v_mul_f32_e32 v62, 0xbfb8aa3b, v62
	v_mul_f32_e32 v63, 0xbfb8aa3b, v63
	v_exp_f32_e32 v62, v62
	v_exp_f32_e32 v63, v63
	v_mul_f32_e32 v60, 0xbfb8aa3b, v60
	v_mul_f32_e32 v61, 0xbfb8aa3b, v61
	v_exp_f32_e32 v60, v60
	v_pk_add_f32 v[62:63], v[62:63], 1.0 op_sel_hi:[1,0]
	v_exp_f32_e32 v61, v61
	s_nop 0
	v_pk_add_f32 v[60:61], v[60:61], 1.0 op_sel_hi:[1,0]
	v_mul_f32_e32 v58, 0xbfb8aa3b, v58
	v_mul_f32_e32 v59, 0xbfb8aa3b, v59
	v_min_f32_e32 v63, 0x7f7fffff, v63
	v_rcp_f32_e32 v64, v63
	s_nop 0
	v_fma_f32 v63, -v63, v64, 1.0
	v_fma_f32 v63, v63, v64, v64
	v_exp_f32_e32 v58, v58
	v_exp_f32_e32 v59, v59
	v_mul_f32_e32 v56, 0xbfb8aa3b, v56
	v_min_f32_e32 v62, 0x7f7fffff, v62
	v_rcp_f32_e32 v64, v62
	s_nop 0
	v_fma_f32 v62, -v62, v64, 1.0
	v_fma_f32 v62, v62, v64, v64
	v_pk_add_f32 v[58:59], v[58:59], 1.0 op_sel_hi:[1,0]
	v_mul_f32_e32 v57, 0xbfb8aa3b, v57
	v_exp_f32_e32 v56, v56
	v_min_f32_e32 v61, 0x7f7fffff, v61
	v_rcp_f32_e32 v64, v61
	s_nop 0
	v_fma_f32 v61, -v61, v64, 1.0
	v_fma_f32 v61, v61, v64, v64
	v_exp_f32_e32 v57, v57
	v_min_f32_e32 v60, 0x7f7fffff, v60
	v_rcp_f32_e32 v64, v60
	s_nop 0
	v_fma_f32 v60, -v60, v64, 1.0
	v_fma_f32 v60, v60, v64, v64
	v_pk_add_f32 v[56:57], v[56:57], 1.0 op_sel_hi:[1,0]
	v_min_f32_e32 v59, 0x7f7fffff, v59
	v_rcp_f32_e32 v64, v59
	s_nop 0
	v_fma_f32 v59, -v59, v64, 1.0
	v_fma_f32 v59, v59, v64, v64
	v_min_f32_e32 v58, 0x7f7fffff, v58
	v_rcp_f32_e32 v64, v58
	s_nop 0
	v_fma_f32 v58, -v58, v64, 1.0
	v_fma_f32 v58, v58, v64, v64
	v_min_f32_e32 v57, 0x7f7fffff, v57
	v_rcp_f32_e32 v64, v57
	s_nop 0
	v_fma_f32 v57, -v57, v64, 1.0
	v_fma_f32 v57, v57, v64, v64
	v_div_scale_f32 v64, s[20:21], v56, v56, 1.0
	v_rcp_f32_e32 v65, v64
	s_nop 0
	v_fma_f32 v66, -v64, v65, 1.0
	v_fmac_f32_e32 v65, v66, v65
	v_div_scale_f32 v66, vcc, 1.0, v56, 1.0
	v_mul_f32_e32 v67, v66, v65
	v_fma_f32 v70, -v64, v67, v66
	v_fmac_f32_e32 v67, v70, v65
	v_fma_f32 v64, -v64, v67, v66
	v_div_fmas_f32 v64, v64, v65, v67
	v_div_fixup_f32 v56, v64, v56, 1.0
	s_and_b64 vcc, exec, s[18:19]
	s_cbranch_vccz .LBB0_291
	s_branch .LBB0_292

.LBB0_361:
	v_mul_f32_e32 v38, 0xbfb8aa3b, v38
	v_mul_f32_e32 v39, 0xbfb8aa3b, v39
	v_exp_f32_e32 v38, v38
	v_exp_f32_e32 v39, v39
	v_mul_f32_e32 v36, 0xbfb8aa3b, v36
	v_mul_f32_e32 v37, 0xbfb8aa3b, v37
	v_exp_f32_e32 v36, v36
	v_pk_add_f32 v[38:39], v[38:39], 1.0 op_sel_hi:[1,0]
	v_exp_f32_e32 v37, v37
	s_nop 0
	v_pk_add_f32 v[36:37], v[36:37], 1.0 op_sel_hi:[1,0]
	v_mul_f32_e32 v34, 0xbfb8aa3b, v34
	v_mul_f32_e32 v35, 0xbfb8aa3b, v35
	v_min_f32_e32 v39, 0x7f7fffff, v39
	v_rcp_f32_e32 v40, v39
	s_nop 0
	v_fma_f32 v39, -v39, v40, 1.0
	v_fma_f32 v39, v39, v40, v40
	v_exp_f32_e32 v34, v34
	v_exp_f32_e32 v35, v35
	v_mul_f32_e32 v32, 0xbfb8aa3b, v32
	v_min_f32_e32 v38, 0x7f7fffff, v38
	v_rcp_f32_e32 v40, v38
	s_nop 0
	v_fma_f32 v38, -v38, v40, 1.0
	v_fma_f32 v38, v38, v40, v40
	v_pk_add_f32 v[34:35], v[34:35], 1.0 op_sel_hi:[1,0]
	v_mul_f32_e32 v33, 0xbfb8aa3b, v33
	v_exp_f32_e32 v32, v32
	v_min_f32_e32 v37, 0x7f7fffff, v37
	v_rcp_f32_e32 v40, v37
	s_nop 0
	v_fma_f32 v37, -v37, v40, 1.0
	v_fma_f32 v37, v37, v40, v40
	v_exp_f32_e32 v33, v33
	v_min_f32_e32 v36, 0x7f7fffff, v36
	v_rcp_f32_e32 v40, v36
	s_nop 0
	v_fma_f32 v36, -v36, v40, 1.0
	v_fma_f32 v36, v36, v40, v40
	v_pk_add_f32 v[32:33], v[32:33], 1.0 op_sel_hi:[1,0]
	v_min_f32_e32 v35, 0x7f7fffff, v35
	v_rcp_f32_e32 v40, v35
	s_nop 0
	v_fma_f32 v35, -v35, v40, 1.0
	v_fma_f32 v35, v35, v40, v40
	v_min_f32_e32 v34, 0x7f7fffff, v34
	v_rcp_f32_e32 v40, v34
	s_nop 0
	v_fma_f32 v34, -v34, v40, 1.0
	v_fma_f32 v34, v34, v40, v40
	v_min_f32_e32 v33, 0x7f7fffff, v33
	v_rcp_f32_e32 v40, v33
	s_nop 0
	v_fma_f32 v33, -v33, v40, 1.0
	v_fma_f32 v33, v33, v40, v40
	v_div_scale_f32 v40, s[20:21], v32, v32, 1.0
	v_rcp_f32_e32 v41, v40
	s_nop 0
	v_fma_f32 v42, -v40, v41, 1.0
	v_fmac_f32_e32 v41, v42, v41
	v_div_scale_f32 v42, vcc, 1.0, v32, 1.0
	v_mul_f32_e32 v43, v42, v41
	v_fma_f32 v46, -v40, v43, v42
	v_fmac_f32_e32 v43, v46, v41
	v_fma_f32 v40, -v40, v43, v42
	v_div_fmas_f32 v40, v40, v41, v43
	v_div_fixup_f32 v32, v40, v32, 1.0
	s_and_b64 vcc, exec, s[18:19]
	s_cbranch_vccz .LBB0_309
	s_branch .LBB0_310

.LBB0_363:
	v_mul_f32_e32 v22, 0xbfb8aa3b, v22
	v_mul_f32_e32 v23, 0xbfb8aa3b, v23
	v_exp_f32_e32 v22, v22
	v_exp_f32_e32 v23, v23
	v_mul_f32_e32 v20, 0xbfb8aa3b, v20
	v_mul_f32_e32 v21, 0xbfb8aa3b, v21
	v_exp_f32_e32 v20, v20
	v_pk_add_f32 v[22:23], v[22:23], 1.0 op_sel_hi:[1,0]
	v_exp_f32_e32 v21, v21
	s_nop 0
	v_pk_add_f32 v[20:21], v[20:21], 1.0 op_sel_hi:[1,0]
	v_mul_f32_e32 v18, 0xbfb8aa3b, v18
	v_mul_f32_e32 v19, 0xbfb8aa3b, v19
	v_min_f32_e32 v23, 0x7f7fffff, v23
	v_rcp_f32_e32 v24, v23
	s_nop 0
	v_fma_f32 v23, -v23, v24, 1.0
	v_fma_f32 v23, v23, v24, v24
	v_exp_f32_e32 v18, v18
	v_exp_f32_e32 v19, v19
	v_mul_f32_e32 v16, 0xbfb8aa3b, v16
	v_min_f32_e32 v22, 0x7f7fffff, v22
	v_rcp_f32_e32 v24, v22
	s_nop 0
	v_fma_f32 v22, -v22, v24, 1.0
	v_fma_f32 v22, v22, v24, v24
	v_pk_add_f32 v[18:19], v[18:19], 1.0 op_sel_hi:[1,0]
	v_mul_f32_e32 v17, 0xbfb8aa3b, v17
	v_exp_f32_e32 v16, v16
	v_min_f32_e32 v21, 0x7f7fffff, v21
	v_rcp_f32_e32 v24, v21
	s_nop 0
	v_fma_f32 v21, -v21, v24, 1.0
	v_fma_f32 v21, v21, v24, v24
	v_exp_f32_e32 v17, v17
	v_min_f32_e32 v20, 0x7f7fffff, v20
	v_rcp_f32_e32 v24, v20
	s_nop 0
	v_fma_f32 v20, -v20, v24, 1.0
	v_fma_f32 v20, v20, v24, v24
	v_pk_add_f32 v[16:17], v[16:17], 1.0 op_sel_hi:[1,0]
	v_min_f32_e32 v19, 0x7f7fffff, v19
	v_rcp_f32_e32 v24, v19
	s_nop 0
	v_fma_f32 v19, -v19, v24, 1.0
	v_fma_f32 v19, v19, v24, v24
	v_min_f32_e32 v18, 0x7f7fffff, v18
	v_rcp_f32_e32 v24, v18
	s_nop 0
	v_fma_f32 v18, -v18, v24, 1.0
	v_fma_f32 v18, v18, v24, v24
	v_min_f32_e32 v17, 0x7f7fffff, v17
	v_rcp_f32_e32 v24, v17
	s_nop 0
	v_fma_f32 v17, -v17, v24, 1.0
	v_fma_f32 v17, v17, v24, v24
	v_div_scale_f32 v24, s[20:21], v16, v16, 1.0
	v_rcp_f32_e32 v25, v24
	s_nop 0
	v_fma_f32 v26, -v24, v25, 1.0
	v_fmac_f32_e32 v25, v26, v25
	v_div_scale_f32 v26, vcc, 1.0, v16, 1.0
	v_mul_f32_e32 v27, v26, v25
	v_fma_f32 v30, -v24, v27, v26
	v_fmac_f32_e32 v27, v30, v25
	v_fma_f32 v24, -v24, v27, v26
	v_div_fmas_f32 v24, v24, v25, v27
	v_div_fixup_f32 v16, v24, v16, 1.0
	s_and_b64 vcc, exec, s[18:19]
	s_cbranch_vccz .LBB0_327
	s_branch .LBB0_328

.LBB0_365:
	v_mul_f32_e32 v6, 0xbfb8aa3b, v6
	v_mul_f32_e32 v7, 0xbfb8aa3b, v7
	v_exp_f32_e32 v6, v6
	v_exp_f32_e32 v7, v7
	v_mul_f32_e32 v4, 0xbfb8aa3b, v4
	v_mul_f32_e32 v5, 0xbfb8aa3b, v5
	v_exp_f32_e32 v4, v4
	v_pk_add_f32 v[6:7], v[6:7], 1.0 op_sel_hi:[1,0]
	v_exp_f32_e32 v5, v5
	s_nop 0
	v_pk_add_f32 v[4:5], v[4:5], 1.0 op_sel_hi:[1,0]
	v_mul_f32_e32 v2, 0xbfb8aa3b, v2
	v_mul_f32_e32 v3, 0xbfb8aa3b, v3
	v_min_f32_e32 v7, 0x7f7fffff, v7
	v_rcp_f32_e32 v8, v7
	s_nop 0
	v_fma_f32 v7, -v7, v8, 1.0
	v_fma_f32 v7, v7, v8, v8
	v_exp_f32_e32 v2, v2
	v_exp_f32_e32 v3, v3
	v_mul_f32_e32 v0, 0xbfb8aa3b, v0
	v_min_f32_e32 v6, 0x7f7fffff, v6
	v_rcp_f32_e32 v8, v6
	s_nop 0
	v_fma_f32 v6, -v6, v8, 1.0
	v_fma_f32 v6, v6, v8, v8
	v_pk_add_f32 v[2:3], v[2:3], 1.0 op_sel_hi:[1,0]
	v_mul_f32_e32 v1, 0xbfb8aa3b, v1
	v_exp_f32_e32 v0, v0
	v_min_f32_e32 v5, 0x7f7fffff, v5
	v_rcp_f32_e32 v8, v5
	s_nop 0
	v_fma_f32 v5, -v5, v8, 1.0
	v_fma_f32 v5, v5, v8, v8
	v_exp_f32_e32 v1, v1
	v_min_f32_e32 v4, 0x7f7fffff, v4
	v_rcp_f32_e32 v8, v4
	s_nop 0
	v_fma_f32 v4, -v4, v8, 1.0
	v_fma_f32 v4, v4, v8, v8
	v_pk_add_f32 v[0:1], v[0:1], 1.0 op_sel_hi:[1,0]
	v_min_f32_e32 v3, 0x7f7fffff, v3
	v_rcp_f32_e32 v8, v3
	s_nop 0
	v_fma_f32 v3, -v3, v8, 1.0
	v_fma_f32 v3, v3, v8, v8
	v_min_f32_e32 v2, 0x7f7fffff, v2
	v_rcp_f32_e32 v8, v2
	s_nop 0
	v_fma_f32 v2, -v2, v8, 1.0
	v_fma_f32 v2, v2, v8, v8
	v_min_f32_e32 v1, 0x7f7fffff, v1
	v_rcp_f32_e32 v8, v1
	s_nop 0
	v_fma_f32 v1, -v1, v8, 1.0
	v_fma_f32 v1, v1, v8, v8
	v_div_scale_f32 v8, s[10:11], v0, v0, 1.0
	v_rcp_f32_e32 v9, v8
	s_nop 0
	v_fma_f32 v10, -v8, v9, 1.0
	v_fmac_f32_e32 v9, v10, v9
	v_div_scale_f32 v10, vcc, 1.0, v0, 1.0
	v_mul_f32_e32 v11, v10, v9
	v_fma_f32 v14, -v8, v11, v10
	v_fmac_f32_e32 v11, v14, v9
	v_fma_f32 v8, -v8, v11, v10
	v_div_fmas_f32 v8, v8, v9, v11
	v_div_fixup_f32 v0, v8, v0, 1.0
	s_and_b64 vcc, exec, s[18:19]
	s_cbranch_vccz .LBB0_345
	s_branch .LBB0_346
